# v27 + GEMM phase prologues: K-tile-1 staging loads issued before the first wait/barrier (one cold round trip per phase instead of two)
# baseline (speedup 1.0000x reference)
; #define PG8_STAGE(bufoff, gbase, voff) do { _Pragma("unroll") for (int _i = 0; _i < 2; ++_i) \
;         __builtin_amdgcn_global_load_lds((const unsigned*)((const char*)(gbase) + (voff)[_i]), (PG8_LAS unsigned*)(lds + (bufoff) + ldsw + _i * 8192), 16, 0, 0); } while (0)
; #define PG8_WAIT_V(n) asm volatile("s_waitcnt vmcnt(" #n ")" ::: "memory")
; #define PG8_BAR __builtin_amdgcn_s_barrier()
; template <class Epi, class Sched, bool ALIGN_EPI = false, bool SP2 = false>
; __device__ __forceinline__ void gemm_phase(PG8_LAS unsigned char* lds, const Gemm g, const Sched& S, const Epi& E, int tid_in) {
;     ...
;     const int wid = __builtin_amdgcn_readfirstlane(tid >> 6), lane = tid & 63, wr = wid >> 2, wc = wid & 3, fr = lane & 15, fq = lane >> 4;
;     const int K = g.K, nt = K / BK;
;     unsigned voffA[2], voffB[2];
; #pragma unroll
;     for (int i = 0; i < 2; ++i) { int R, C; stage_rc(tid * 16 + i * 8192, R, C); const int Rb = Epi::PERM ? ((R & ~31) + perm32(R & 31)) : R;
;         voffA[i] = (unsigned)(R * K + C) * 2u; voffB[i] = (unsigned)(Rb * K + C) * 2u; }
;     const size_t kstep = (size_t)(BK * 2);
;     const size_t hstep = (size_t)HALF * K * 2;
;     const size_t tstep = 2 * hstep;
;     const unsigned ldsw = (unsigned)wid * 1024u;
;     const int aoff = lds_byte(wr * 64 + fr, fq * 8), boff = lds_byte(wc * 32 + fr, fq * 8);
;     ...
;     if constexpr (SP2) {
;         PG8_STAGE(PG8_SB(0, 0), cB, voffB); PG8_STAGE(PG8_SB(0, 1), cB + hstep, voffB); PG8_STAGE(PG8_SA(0, 0), cA, voffA); PG8_STAGE(PG8_SA(0, 1), cA + hstep, voffA);
;         if (wr == 1) PG8_BAR;
;         PG8_WAIT_V(2); PG8_BAR;
;         PG8_STAGE(PG8_SB(1, 0), cB + kstep, voffB); PG8_STAGE(PG8_SA(1, 0), cA + kstep, voffA); PG8_STAGE(PG8_SB(1, 1), cB + hstep + kstep, voffB);
;         PG8_WAIT_V(6); PG8_BAR;
.LBB0_106:
	s_mov_b64 s[10:11], 0x80
	s_and_b32 s0, s0, 3
	s_add_i32 m0, s63, 0x18000
	v_lshl_add_u64 v[6:7], v[6:7], 0, s[10:11]
	s_lshl_b32 s23, s1, 13
	s_lshl_b32 s36, s0, 12
	global_load_lds_dwordx4 v[6:7], off
	v_lshl_add_u64 v[4:5], v[4:5], 0, s[10:11]
	s_add_i32 m0, s63, 0x1a000
	s_add_i32 s75, s63, 0x8000
	s_add_i32 s76, s63, 0xa000
	global_load_lds_dwordx4 v[4:5], off
	v_lshl_add_u64 v[0:1], v[0:1], 0, s[10:11]
	s_mov_b32 m0, s75
	s_add_u32 s24, s66, 0x40080
	global_load_lds_dwordx4 v[0:1], off
	v_lshl_add_u64 v[0:1], v[2:3], 0, s[10:11]
	s_mov_b32 m0, s76
	s_addc_u32 s25, s67, 0
	global_load_lds_dwordx4 v[0:1], off
	s_add_i32 m0, s63, 0x1c000
	v_lshl_add_u64 v[0:1], s[24:25], 0, v[130:131]
	global_load_lds_dwordx4 v[0:1], off
	v_lshl_add_u64 v[0:1], s[24:25], 0, v[134:135]
	s_add_i32 m0, s63, 0x1e000
	s_cmpk_lt_u32 s22, 0x100
	global_load_lds_dwordx4 v[0:1], off
	s_waitcnt vmcnt(8)
	s_barrier
	v_lshrrev_b32_e32 v1, 1, v8
	v_and_b32_e32 v138, 24, v1
	v_and_b32_e32 v0, 15, v8
	v_lshlrev_b32_e32 v1, 1, v138
	v_lshl_or_b32 v139, s1, 6, v0
	v_lshl_or_b32 v0, v0, 6, v1
	v_lshlrev_b32_e32 v1, 2, v8
	v_and_b32_e32 v1, 32, v1
	v_bitop3_b32 v2, v0, s23, v1 bitop3:0xde
	v_bitop3_b32 v172, v0, s36, v1 bitop3:0xde
	v_add_u32_e32 v0, 64, v169
	v_cmp_lt_i32_e32 vcc, v228, v0
	s_waitcnt vmcnt(6)
	s_cselect_b64 s[22:23], -1, 0
	s_lshl_b32 s0, s0, 6
	v_cndmask_b32_e32 v1, v219, v228, vcc
	v_cmp_lt_i32_e32 vcc, v171, v0
	v_lshlrev_b32_e32 v173, 2, v1
	v_and_b32_e32 v1, 1, v9
	v_cndmask_b32_e32 v0, v219, v171, vcc
	v_lshlrev_b32_e32 v174, 2, v0
	v_lshlrev_b32_e32 v0, 14, v9
	v_and_b32_e32 v0, 0xffff8000, v0
	v_lshl_add_u32 v0, v10, 11, v0
	v_lshl_or_b32 v0, v1, 6, v0
	v_lshl_add_u32 v140, v11, 1, v0
	v_lshlrev_b32_e32 v0, 14, v12
	v_and_b32_e32 v0, 0xffff8000, v0
	v_lshl_add_u32 v0, v13, 11, v0
	v_and_b32_e32 v1, 1, v12
	v_lshl_or_b32 v0, v1, 6, v0
	s_add_i32 s79, 0, 0x10000
	s_add_i32 s80, 0, 0x14000
	s_ashr_i32 s77, s3, 31
	s_ashr_i32 s78, s2, 31
	v_mov_b32_e32 v141, v137
	v_lshl_add_u32 v142, v14, 1, v0
	v_mov_b32_e32 v143, v137
	v_mov_b64_e32 v[144:145], 0x800
	v_mov_b64_e32 v[146:147], 0x7ff
	v_add_u32_e32 v175, s79, v172
	v_add_u32_e32 v176, s80, v172
	v_add_u32_e32 v177, 0, v2
	v_lshlrev_b32_e32 v136, 2, v138
	v_mov_b32_e32 v178, 0x358637bd
	s_mov_b32 s81, 0x800000
	s_lshl_b32 s82, s0, 1
	s_mov_b64 s[24:25], 0x80000
	s_mov_b32 s83, 0x80000
	s_mov_b64 s[36:37], 0x90000
	s_mov_b32 s84, 0x90000
	s_mov_b64 s[38:39], 0xa0000
	s_mov_b32 s85, 0xa0000
	s_mov_b64 s[40:41], 0xb0000
	s_mov_b32 s86, 0xb0000
	v_mov_b32_e32 v179, 0x3e38aa3b
	s_barrier
	s_branch .LBB0_109

; #define PG8_STAGE(bufoff, gbase, voff) do { _Pragma("unroll") for (int _i = 0; _i < 2; ++_i) \
;         __builtin_amdgcn_global_load_lds((const unsigned*)((const char*)(gbase) + (voff)[_i]), (PG8_LAS unsigned*)(lds + (bufoff) + ldsw + _i * 8192), 16, 0, 0); } while (0)
; #define PG8_WAIT_V(n) asm volatile("s_waitcnt vmcnt(" #n ")" ::: "memory")
; #define PG8_BAR __builtin_amdgcn_s_barrier()
; template <class Epi, class Sched, bool ALIGN_EPI = false, bool SP2 = false>
; __device__ __forceinline__ void gemm_phase(PG8_LAS unsigned char* lds, const Gemm g, const Sched& S, const Epi& E, int tid_in) {
;     ...
;     const int wid = __builtin_amdgcn_readfirstlane(tid >> 6), lane = tid & 63, wr = wid >> 2, wc = wid & 3, fr = lane & 15, fq = lane >> 4;
;     const int K = g.K, nt = K / BK;
;     unsigned voffA[2], voffB[2];
; #pragma unroll
;     for (int i = 0; i < 2; ++i) { int R, C; stage_rc(tid * 16 + i * 8192, R, C); const int Rb = Epi::PERM ? ((R & ~31) + perm32(R & 31)) : R;
;         voffA[i] = (unsigned)(R * K + C) * 2u; voffB[i] = (unsigned)(Rb * K + C) * 2u; }
;     const size_t kstep = (size_t)(BK * 2);
;     const size_t hstep = (size_t)HALF * K * 2;
;     const size_t tstep = 2 * hstep;
;     const unsigned ldsw = (unsigned)wid * 1024u;
;     const int aoff = lds_byte(wr * 64 + fr, fq * 8), boff = lds_byte(wc * 32 + fr, fq * 8);
;     ...
;     if constexpr (SP2) {
;         PG8_STAGE(PG8_SB(0, 0), cB, voffB); PG8_STAGE(PG8_SB(0, 1), cB + hstep, voffB); PG8_STAGE(PG8_SA(0, 0), cA, voffA); PG8_STAGE(PG8_SA(0, 1), cA + hstep, voffA);
;         if (wr == 1) PG8_BAR;
;         PG8_WAIT_V(2); PG8_BAR;
;         PG8_STAGE(PG8_SB(1, 0), cB + kstep, voffB); PG8_STAGE(PG8_SA(1, 0), cA + kstep, voffA); PG8_STAGE(PG8_SB(1, 1), cB + hstep + kstep, voffB);
;         PG8_WAIT_V(6); PG8_BAR;
.LBB0_156:
	s_mov_b64 s[22:23], 0x80
	s_and_b32 s9, s9, 3
	s_add_i32 m0, s65, 0x18000
	v_lshl_add_u64 v[6:7], v[6:7], 0, s[22:23]
	s_lshl_b32 s25, s24, 13
	s_lshl_b32 s38, s9, 12
	global_load_lds_dwordx4 v[6:7], off
	v_lshl_add_u64 v[4:5], v[4:5], 0, s[22:23]
	s_add_i32 m0, s65, 0x1a000
	s_add_i32 s79, s65, 0x8000
	s_add_i32 s80, s65, 0xa000
	global_load_lds_dwordx4 v[4:5], off
	v_lshl_add_u64 v[0:1], v[0:1], 0, s[22:23]
	s_mov_b32 m0, s79
	s_add_u32 s36, s70, 0x40080
	global_load_lds_dwordx4 v[0:1], off
	v_lshl_add_u64 v[0:1], v[2:3], 0, s[22:23]
	s_mov_b32 m0, s80
	s_addc_u32 s37, s71, 0
	global_load_lds_dwordx4 v[0:1], off
	s_add_i32 m0, s65, 0x1c000
	v_lshl_add_u64 v[0:1], s[36:37], 0, v[130:131]
	global_load_lds_dwordx4 v[0:1], off
	v_lshl_add_u64 v[0:1], s[36:37], 0, v[134:135]
	s_add_i32 m0, s65, 0x1e000
	s_cmpk_lt_u32 s8, 0x100
	global_load_lds_dwordx4 v[0:1], off
	s_waitcnt vmcnt(8)
	s_barrier
	v_lshrrev_b32_e32 v1, 1, v8
	v_and_b32_e32 v138, 24, v1
	v_and_b32_e32 v0, 15, v8
	v_lshlrev_b32_e32 v1, 1, v138
	v_lshl_or_b32 v139, s24, 6, v0
	v_lshl_or_b32 v0, v0, 6, v1
	v_lshlrev_b32_e32 v1, 2, v8
	v_and_b32_e32 v1, 32, v1
	v_bitop3_b32 v2, v0, s25, v1 bitop3:0xde
	v_bitop3_b32 v172, v0, s38, v1 bitop3:0xde
	v_add_u32_e32 v0, 64, v169
	v_cmp_lt_i32_e32 vcc, v228, v0
	s_waitcnt vmcnt(6)
	s_cselect_b64 s[24:25], -1, 0
	s_lshl_b32 s8, s9, 6
	v_cndmask_b32_e32 v1, v219, v228, vcc
	v_cmp_lt_i32_e32 vcc, v171, v0
	v_lshlrev_b32_e32 v173, 2, v1
	v_and_b32_e32 v1, 1, v9
	v_cndmask_b32_e32 v0, v219, v171, vcc
	v_lshlrev_b32_e32 v174, 2, v0
	v_lshlrev_b32_e32 v0, 14, v9
	v_and_b32_e32 v0, 0xffff8000, v0
	v_lshl_add_u32 v0, v10, 11, v0
	v_lshl_or_b32 v0, v1, 6, v0
	v_lshl_add_u32 v140, v11, 1, v0
	v_lshlrev_b32_e32 v0, 14, v12
	v_and_b32_e32 v0, 0xffff8000, v0
	v_lshl_add_u32 v0, v13, 11, v0
	v_and_b32_e32 v1, 1, v12
	v_lshl_or_b32 v0, v1, 6, v0
	s_add_i32 s83, 0, 0x10000
	s_add_i32 s84, 0, 0x14000
	s_ashr_i32 s81, s3, 31
	s_ashr_i32 s82, s2, 31
	v_mov_b32_e32 v141, v137
	v_lshl_add_u32 v142, v14, 1, v0
	v_mov_b32_e32 v143, v137
	v_mov_b64_e32 v[144:145], 0x400
	v_mov_b64_e32 v[146:147], 0x3ff
	v_add_u32_e32 v175, s83, v172
	v_add_u32_e32 v176, s84, v172
	v_add_u32_e32 v177, 0, v2
	v_lshlrev_b32_e32 v136, 2, v138
	v_mov_b32_e32 v178, 0x358637bd
	s_mov_b32 s85, 0x800000
	s_lshl_b32 s86, s8, 1
	s_mov_b64 s[36:37], 0x80000
	s_mov_b32 s87, 0x80000
	s_mov_b64 s[38:39], 0x90000
	s_mov_b32 s88, 0x90000
	s_mov_b64 s[40:41], 0xa0000
	s_mov_b32 s89, 0xa0000
	s_mov_b64 s[42:43], 0xb0000
	s_mov_b32 s90, 0xb0000
	v_mov_b32_e32 v179, 0x3e38aa3b
	s_barrier
	s_branch .LBB0_159

; #define PG8_STAGE(bufoff, gbase, voff) do { _Pragma("unroll") for (int _i = 0; _i < 2; ++_i) \
;         __builtin_amdgcn_global_load_lds((const unsigned*)((const char*)(gbase) + (voff)[_i]), (PG8_LAS unsigned*)(lds + (bufoff) + ldsw + _i * 8192), 16, 0, 0); } while (0)
; #define PG8_WAIT_V(n) asm volatile("s_waitcnt vmcnt(" #n ")" ::: "memory")
; #define PG8_BAR __builtin_amdgcn_s_barrier()
; template <class Epi, class Sched, bool ALIGN_EPI = false, bool SP2 = false>
; __device__ __forceinline__ void gemm_phase(PG8_LAS unsigned char* lds, const Gemm g, const Sched& S, const Epi& E, int tid_in) {
;     ...
;     const int wid = __builtin_amdgcn_readfirstlane(tid >> 6), lane = tid & 63, wr = wid >> 2, wc = wid & 3, fr = lane & 15, fq = lane >> 4;
;     const int K = g.K, nt = K / BK;
;     unsigned voffA[2], voffB[2];
; #pragma unroll
;     for (int i = 0; i < 2; ++i) { int R, C; stage_rc(tid * 16 + i * 8192, R, C); const int Rb = Epi::PERM ? ((R & ~31) + perm32(R & 31)) : R;
;         voffA[i] = (unsigned)(R * K + C) * 2u; voffB[i] = (unsigned)(Rb * K + C) * 2u; }
;     const size_t kstep = (size_t)(BK * 2);
;     const size_t hstep = (size_t)HALF * K * 2;
;     const size_t tstep = 2 * hstep;
;     const unsigned ldsw = (unsigned)wid * 1024u;
;     const int aoff = lds_byte(wr * 64 + fr, fq * 8), boff = lds_byte(wc * 32 + fr, fq * 8);
;     ...
;     if constexpr (SP2) {
;         PG8_STAGE(PG8_SB(0, 0), cB, voffB); PG8_STAGE(PG8_SB(0, 1), cB + hstep, voffB); PG8_STAGE(PG8_SA(0, 0), cA, voffA); PG8_STAGE(PG8_SA(0, 1), cA + hstep, voffA);
;         if (wr == 1) PG8_BAR;
;         PG8_WAIT_V(2); PG8_BAR;
;         PG8_STAGE(PG8_SB(1, 0), cB + kstep, voffB); PG8_STAGE(PG8_SA(1, 0), cA + kstep, voffA); PG8_STAGE(PG8_SB(1, 1), cB + hstep + kstep, voffB);
;         PG8_WAIT_V(6); PG8_BAR;
.LBB0_204:
	s_lshl_b32 s10, s10, 5
	s_and_b32 s22, s10, 0x60
	s_mov_b64 s[10:11], 0x80
	s_add_i32 m0, s61, 0x18000
	v_lshl_add_u64 v[6:7], v[6:7], 0, s[10:11]
	s_lshl_b32 s19, s7, 13
	s_lshl_b32 s23, s22, 7
	global_load_lds_dwordx4 v[6:7], off
	v_lshl_add_u64 v[4:5], v[4:5], 0, s[10:11]
	s_add_i32 m0, s61, 0x1a000
	s_add_i32 s77, s61, 0x8000
	s_add_i32 s78, s61, 0xa000
	global_load_lds_dwordx4 v[4:5], off
	v_lshl_add_u64 v[0:1], v[0:1], 0, s[10:11]
	s_mov_b32 m0, s77
	s_add_u32 s20, s64, 0x40080
	global_load_lds_dwordx4 v[0:1], off
	v_lshl_add_u64 v[0:1], v[2:3], 0, s[10:11]
	s_mov_b32 m0, s78
	s_addc_u32 s21, s65, 0
	global_load_lds_dwordx4 v[0:1], off
	s_add_i32 m0, s61, 0x1c000
	v_lshl_add_u64 v[0:1], s[20:21], 0, v[130:131]
	global_load_lds_dwordx4 v[0:1], off
	v_lshl_add_u64 v[0:1], s[20:21], 0, v[134:135]
	s_add_i32 m0, s61, 0x1e000
	s_cmpk_lt_u32 s18, 0x100
	global_load_lds_dwordx4 v[0:1], off
	s_waitcnt vmcnt(8)
	s_barrier
	v_lshrrev_b32_e32 v1, 1, v8
	v_and_b32_e32 v1, 24, v1
	v_and_b32_e32 v0, 15, v8
	v_lshlrev_b32_e32 v2, 1, v1
	v_lshl_or_b32 v148, s7, 6, v0
	v_lshl_or_b32 v0, v0, 6, v2
	v_lshlrev_b32_e32 v2, 2, v8
	v_and_b32_e32 v2, 32, v2
	v_bitop3_b32 v3, v0, s19, v2 bitop3:0xde
	v_bitop3_b32 v149, v0, s23, v2 bitop3:0xde
	v_lshlrev_b32_e32 v0, 14, v9
	v_and_b32_e32 v0, 0xffff8000, v0
	v_or_b32_e32 v150, s22, v1
	v_lshl_add_u32 v0, v10, 11, v0
	v_and_b32_e32 v1, 1, v9
	v_lshl_or_b32 v0, v1, 6, v0
	v_lshl_add_u32 v138, v11, 1, v0
	v_lshlrev_b32_e32 v0, 14, v12
	v_and_b32_e32 v0, 0xffff8000, v0
	s_waitcnt vmcnt(6)
	v_lshl_add_u32 v0, v13, 11, v0
	v_and_b32_e32 v1, 1, v12
	s_cselect_b64 s[18:19], -1, 0
	v_lshl_or_b32 v0, v1, 6, v0
	s_add_i32 s80, 0, 0x10000
	s_add_i32 s81, 0, 0x14000
	s_sext_i32_i16 s86, s6
	s_ashr_i32 s79, s3, 31
	v_mov_b32_e32 v139, v137
	v_lshl_add_u32 v140, v14, 1, v0
	v_mov_b32_e32 v141, v137
	v_mov_b64_e32 v[142:143], 0x400
	v_mov_b64_e32 v[144:145], 0x3ff
	v_add_u32_e32 v151, s80, v149
	v_add_u32_e32 v152, s81, v149
	v_add_u32_e32 v153, 0, v3
	s_mov_b64 s[20:21], 0x100000
	s_mov_b32 s82, 0x100000
	s_mov_b64 s[22:23], 0x120000
	s_mov_b32 s83, 0x120000
	s_mov_b64 s[24:25], 0x140000
	s_mov_b32 s84, 0x140000
	s_mov_b64 s[38:39], 0x160000
	s_mov_b32 s85, 0x160000
	s_barrier
	s_branch .LBB0_207

; #define PG8_STAGE(bufoff, gbase, voff) do { _Pragma("unroll") for (int _i = 0; _i < 2; ++_i) \
;         __builtin_amdgcn_global_load_lds((const unsigned*)((const char*)(gbase) + (voff)[_i]), (PG8_LAS unsigned*)(lds + (bufoff) + ldsw + _i * 8192), 16, 0, 0); } while (0)
; #define PG8_WAIT_V(n) asm volatile("s_waitcnt vmcnt(" #n ")" ::: "memory")
; #define PG8_BAR __builtin_amdgcn_s_barrier()
; template <class Epi, class Sched, bool ALIGN_EPI = false, bool SP2 = false>
; __device__ __forceinline__ void gemm_phase(PG8_LAS unsigned char* lds, const Gemm g, const Sched& S, const Epi& E, int tid_in) {
;     ...
;     const int wid = __builtin_amdgcn_readfirstlane(tid >> 6), lane = tid & 63, wr = wid >> 2, wc = wid & 3, fr = lane & 15, fq = lane >> 4;
;     const int K = g.K, nt = K / BK;
;     unsigned voffA[2], voffB[2];
; #pragma unroll
;     for (int i = 0; i < 2; ++i) { int R, C; stage_rc(tid * 16 + i * 8192, R, C); const int Rb = Epi::PERM ? ((R & ~31) + perm32(R & 31)) : R;
;         voffA[i] = (unsigned)(R * K + C) * 2u; voffB[i] = (unsigned)(Rb * K + C) * 2u; }
;     const size_t kstep = (size_t)(BK * 2);
;     const size_t hstep = (size_t)HALF * K * 2;
;     const size_t tstep = 2 * hstep;
;     const unsigned ldsw = (unsigned)wid * 1024u;
;     const int aoff = lds_byte(wr * 64 + fr, fq * 8), boff = lds_byte(wc * 32 + fr, fq * 8);
;     ...
;     if constexpr (SP2) {
;         PG8_STAGE(PG8_SB(0, 0), cB, voffB); PG8_STAGE(PG8_SB(0, 1), cB + hstep, voffB); PG8_STAGE(PG8_SA(0, 0), cA, voffA); PG8_STAGE(PG8_SA(0, 1), cA + hstep, voffA);
;         if (wr == 1) PG8_BAR;
;         PG8_WAIT_V(2); PG8_BAR;
;         PG8_STAGE(PG8_SB(1, 0), cB + kstep, voffB); PG8_STAGE(PG8_SA(1, 0), cA + kstep, voffA); PG8_STAGE(PG8_SB(1, 1), cB + hstep + kstep, voffB);
;         PG8_WAIT_V(6); PG8_BAR;
.LBB0_292:
	s_lshl_b32 s9, s9, 5
	s_mov_b64 s[20:21], 0x80
	s_and_b32 s40, s9, 0x60
	s_add_i32 m0, s59, 0x18000
	v_lshl_add_u64 v[6:7], v[6:7], 0, s[20:21]
	s_lshl_b32 s11, s8, 13
	s_lshl_b32 s9, s40, 7
	global_load_lds_dwordx4 v[6:7], off
	v_lshl_add_u64 v[4:5], v[4:5], 0, s[20:21]
	s_add_i32 m0, s59, 0x1a000
	s_add_i32 s76, s59, 0x8000
	s_add_i32 s77, s59, 0xa000
	global_load_lds_dwordx4 v[4:5], off
	v_lshl_add_u64 v[0:1], v[0:1], 0, s[20:21]
	s_mov_b32 m0, s76
	s_add_u32 s22, s62, 0x80080
	global_load_lds_dwordx4 v[0:1], off
	v_lshl_add_u64 v[0:1], v[2:3], 0, s[20:21]
	s_mov_b32 m0, s77
	s_addc_u32 s23, s63, 0
	global_load_lds_dwordx4 v[0:1], off
	s_add_i32 m0, s59, 0x1c000
	v_lshl_add_u64 v[0:1], s[22:23], 0, v[130:131]
	global_load_lds_dwordx4 v[0:1], off
	v_lshl_add_u64 v[0:1], s[22:23], 0, v[134:135]
	s_add_i32 m0, s59, 0x1e000
	v_cmp_lt_i32_e32 vcc, v228, v221
	global_load_lds_dwordx4 v[0:1], off
	s_waitcnt vmcnt(8)
	s_barrier
	v_bfe_u32 v1, v8, 4, 2
	v_and_b32_e32 v0, 15, v8
	v_lshlrev_b32_e32 v2, 4, v1
	v_lshl_or_b32 v150, s8, 6, v0
	v_lshl_or_b32 v0, v0, 6, v2
	v_lshlrev_b32_e32 v2, 2, v8
	v_and_b32_e32 v2, 32, v2
	v_bitop3_b32 v3, v0, s11, v2 bitop3:0xde
	v_bitop3_b32 v151, v0, s9, v2 bitop3:0xde
	v_cndmask_b32_e32 v0, v219, v228, vcc
	v_lshlrev_b32_e32 v152, 2, v0
	v_lshlrev_b32_e32 v0, 15, v9
	v_and_b32_e32 v0, 0xffff0000, v0
	v_cmp_eq_u32_e64 s[8:9], 0, v1
	v_lshl_or_b32 v153, v1, 3, s40
	v_lshl_add_u32 v0, v10, 12, v0
	v_and_b32_e32 v1, 1, v9
	v_lshl_or_b32 v0, v1, 6, v0
	v_lshl_add_u32 v138, v11, 1, v0
	v_lshlrev_b32_e32 v0, 15, v12
	v_and_b32_e32 v0, 0xffff0000, v0
	s_waitcnt vmcnt(6)
	s_cmpk_lt_u32 s10, 0x100
	v_lshl_add_u32 v0, v13, 12, v0
	v_and_b32_e32 v1, 1, v12
	s_cselect_b64 s[22:23], -1, 0
	v_lshl_or_b32 v0, v1, 6, v0
	s_add_i32 s80, 0, 0x10000
	s_add_i32 s81, 0, 0x14000
	s_ashr_i32 s78, s3, 31
	s_ashr_i32 s79, s2, 31
	v_mov_b32_e32 v139, v131
	v_lshl_add_u32 v140, v14, 1, v0
	v_mov_b32_e32 v141, v131
	v_mov_b64_e32 v[142:143], 0x200
	v_mov_b64_e32 v[144:145], 0x1ff
	v_add_u32_e32 v154, s80, v151
	v_add_u32_e32 v155, s81, v151
	v_add_u32_e32 v156, 0, v3
	s_barrier
	s_branch .LBB0_295

; #define PG8_STAGE(bufoff, gbase, voff) do { _Pragma("unroll") for (int _i = 0; _i < 2; ++_i) \
;         __builtin_amdgcn_global_load_lds((const unsigned*)((const char*)(gbase) + (voff)[_i]), (PG8_LAS unsigned*)(lds + (bufoff) + ldsw + _i * 8192), 16, 0, 0); } while (0)
; #define PG8_WAIT_V(n) asm volatile("s_waitcnt vmcnt(" #n ")" ::: "memory")
; #define PG8_BAR __builtin_amdgcn_s_barrier()
; template <class Epi, class Sched, bool ALIGN_EPI = false, bool SP2 = false>
; __device__ __forceinline__ void gemm_phase(PG8_LAS unsigned char* lds, const Gemm g, const Sched& S, const Epi& E, int tid_in) {
;     ...
;     const int wid = __builtin_amdgcn_readfirstlane(tid >> 6), lane = tid & 63, wr = wid >> 2, wc = wid & 3, fr = lane & 15, fq = lane >> 4;
;     const int K = g.K, nt = K / BK;
;     unsigned voffA[2], voffB[2];
; #pragma unroll
;     for (int i = 0; i < 2; ++i) { int R, C; stage_rc(tid * 16 + i * 8192, R, C); const int Rb = Epi::PERM ? ((R & ~31) + perm32(R & 31)) : R;
;         voffA[i] = (unsigned)(R * K + C) * 2u; voffB[i] = (unsigned)(Rb * K + C) * 2u; }
;     const size_t kstep = (size_t)(BK * 2);
;     const size_t hstep = (size_t)HALF * K * 2;
;     const size_t tstep = 2 * hstep;
;     const unsigned ldsw = (unsigned)wid * 1024u;
;     const int aoff = lds_byte(wr * 64 + fr, fq * 8), boff = lds_byte(wc * 32 + fr, fq * 8);
;     ...
;     if constexpr (SP2) {
;         PG8_STAGE(PG8_SB(0, 0), cB, voffB); PG8_STAGE(PG8_SB(0, 1), cB + hstep, voffB); PG8_STAGE(PG8_SA(0, 0), cA, voffA); PG8_STAGE(PG8_SA(0, 1), cA + hstep, voffA);
;         if (wr == 1) PG8_BAR;
;         PG8_WAIT_V(2); PG8_BAR;
;         PG8_STAGE(PG8_SB(1, 0), cB + kstep, voffB); PG8_STAGE(PG8_SA(1, 0), cA + kstep, voffA); PG8_STAGE(PG8_SB(1, 1), cB + hstep + kstep, voffB);
;         PG8_WAIT_V(6); PG8_BAR;
.LBB0_342:
	s_lshl_b32 s5, s5, 5
	s_mov_b64 s[18:19], 0x80
	s_and_b32 s5, s5, 0x60
	s_add_i32 m0, s74, 0x18000
	v_lshl_add_u64 v[6:7], v[6:7], 0, s[18:19]
	s_lshl_b32 s9, s4, 13
	s_lshl_b32 s11, s5, 7
	global_load_lds_dwordx4 v[6:7], off
	v_lshl_add_u64 v[4:5], v[4:5], 0, s[18:19]
	s_add_i32 m0, s74, 0x1a000
	s_add_i32 s79, s74, 0x8000
	s_add_i32 s80, s74, 0xa000
	global_load_lds_dwordx4 v[4:5], off
	v_lshl_add_u64 v[0:1], v[0:1], 0, s[18:19]
	s_mov_b32 m0, s79
	s_add_u32 s22, s64, 0x40080
	global_load_lds_dwordx4 v[0:1], off
	v_lshl_add_u64 v[0:1], v[2:3], 0, s[18:19]
	s_mov_b32 m0, s80
	s_addc_u32 s23, s65, 0
	global_load_lds_dwordx4 v[0:1], off
	s_add_i32 m0, s74, 0x1c000
	v_lshl_add_u64 v[0:1], s[22:23], 0, v[130:131]
	global_load_lds_dwordx4 v[0:1], off
	v_lshl_add_u64 v[0:1], s[22:23], 0, v[134:135]
	s_add_i32 m0, s74, 0x1e000
	s_cmpk_lt_u32 s20, 0x100
	global_load_lds_dwordx4 v[0:1], off
	s_waitcnt vmcnt(8)
	s_barrier
	v_lshrrev_b32_e32 v1, 1, v8
	v_and_b32_e32 v1, 24, v1
	v_and_b32_e32 v0, 15, v8
	v_lshlrev_b32_e32 v2, 1, v1
	v_lshl_or_b32 v158, s4, 6, v0
	v_lshl_or_b32 v0, v0, 6, v2
	v_lshlrev_b32_e32 v2, 2, v8
	v_and_b32_e32 v2, 32, v2
	v_bitop3_b32 v3, v0, s9, v2 bitop3:0xde
	v_bitop3_b32 v159, v0, s11, v2 bitop3:0xde
	v_lshlrev_b32_e32 v0, 14, v9
	v_and_b32_e32 v0, 0xffff8000, v0
	v_or_b32_e32 v160, s5, v1
	v_lshl_add_u32 v0, v10, 11, v0
	v_and_b32_e32 v1, 1, v9
	v_lshl_or_b32 v0, v1, 6, v0
	v_lshl_add_u32 v140, v11, 1, v0
	v_lshlrev_b32_e32 v0, 14, v12
	v_and_b32_e32 v0, 0xffff8000, v0
	s_waitcnt vmcnt(6)
	v_lshl_add_u32 v0, v13, 11, v0
	v_and_b32_e32 v1, 1, v12
	s_cselect_b64 s[20:21], -1, 0
	v_lshl_or_b32 v0, v1, 6, v0
	s_add_i32 s83, 0, 0x10000
	s_add_i32 s84, 0, 0x14000
	s_ashr_i32 s81, s3, 31
	s_ashr_i32 s82, s2, 31
	v_mov_b32_e32 v141, v139
	v_lshl_add_u32 v142, v14, 1, v0
	v_mov_b32_e32 v143, v139
	v_mov_b64_e32 v[144:145], 0x800
	v_mov_b64_e32 v[146:147], 0x7ff
	v_add_u32_e32 v161, s83, v159
	v_add_u32_e32 v162, s84, v159
	v_add_u32_e32 v163, 0, v3
	v_mov_b32_e32 v164, 0x358637bd
	s_mov_b32 s85, 0x800000
	s_mov_b64 s[22:23], 0x80000
	s_mov_b32 s86, 0x80000
	s_mov_b64 s[40:41], 0x90000
	s_mov_b32 s87, 0x90000
	s_mov_b64 s[42:43], 0xa0000
	s_mov_b32 s88, 0xa0000
	s_mov_b64 s[52:53], 0xb0000
	s_mov_b32 s89, 0xb0000
	s_barrier
	s_branch .LBB0_345

; #define PG8_STAGE(bufoff, gbase, voff) do { _Pragma("unroll") for (int _i = 0; _i < 2; ++_i) \
;         __builtin_amdgcn_global_load_lds((const unsigned*)((const char*)(gbase) + (voff)[_i]), (PG8_LAS unsigned*)(lds + (bufoff) + ldsw + _i * 8192), 16, 0, 0); } while (0)
; #define PG8_WAIT_V(n) asm volatile("s_waitcnt vmcnt(" #n ")" ::: "memory")
; #define PG8_BAR __builtin_amdgcn_s_barrier()
; template <class Epi, class Sched, bool ALIGN_EPI = false, bool SP2 = false>
; __device__ __forceinline__ void gemm_phase(PG8_LAS unsigned char* lds, const Gemm g, const Sched& S, const Epi& E, int tid_in) {
;     ...
;     const int wid = __builtin_amdgcn_readfirstlane(tid >> 6), lane = tid & 63, wr = wid >> 2, wc = wid & 3, fr = lane & 15, fq = lane >> 4;
;     const int K = g.K, nt = K / BK;
;     unsigned voffA[2], voffB[2];
; #pragma unroll
;     for (int i = 0; i < 2; ++i) { int R, C; stage_rc(tid * 16 + i * 8192, R, C); const int Rb = Epi::PERM ? ((R & ~31) + perm32(R & 31)) : R;
;         voffA[i] = (unsigned)(R * K + C) * 2u; voffB[i] = (unsigned)(Rb * K + C) * 2u; }
;     const size_t kstep = (size_t)(BK * 2);
;     const size_t hstep = (size_t)HALF * K * 2;
;     const size_t tstep = 2 * hstep;
;     const unsigned ldsw = (unsigned)wid * 1024u;
;     const int aoff = lds_byte(wr * 64 + fr, fq * 8), boff = lds_byte(wc * 32 + fr, fq * 8);
;     ...
;     if constexpr (SP2) {
;         PG8_STAGE(PG8_SB(0, 0), cB, voffB); PG8_STAGE(PG8_SB(0, 1), cB + hstep, voffB); PG8_STAGE(PG8_SA(0, 0), cA, voffA); PG8_STAGE(PG8_SA(0, 1), cA + hstep, voffA);
;         if (wr == 1) PG8_BAR;
;         PG8_WAIT_V(2); PG8_BAR;
;         PG8_STAGE(PG8_SB(1, 0), cB + kstep, voffB); PG8_STAGE(PG8_SA(1, 0), cA + kstep, voffA); PG8_STAGE(PG8_SB(1, 1), cB + hstep + kstep, voffB);
;         PG8_WAIT_V(6); PG8_BAR;
.LBB0_442:
	s_lshl_b32 s8, s8, 5
	s_and_b32 s14, s8, 0x60
	s_mov_b64 s[8:9], 0x80
	s_add_i32 m0, s45, 0x18000
	v_lshl_add_u64 v[6:7], v[6:7], 0, s[8:9]
	s_lshl_b32 s11, s1, 13
	s_lshl_b32 s15, s14, 7
	global_load_lds_dwordx4 v[6:7], off
	v_lshl_add_u64 v[4:5], v[4:5], 0, s[8:9]
	s_add_i32 m0, s45, 0x1a000
	s_add_i32 s61, s45, 0x8000
	s_add_i32 s62, s45, 0xa000
	global_load_lds_dwordx4 v[4:5], off
	v_lshl_add_u64 v[0:1], v[0:1], 0, s[8:9]
	s_mov_b32 m0, s61
	s_add_u32 s12, s50, 0x80080
	global_load_lds_dwordx4 v[0:1], off
	v_lshl_add_u64 v[0:1], v[2:3], 0, s[8:9]
	s_mov_b32 m0, s62
	s_addc_u32 s13, s51, 0
	global_load_lds_dwordx4 v[0:1], off
	s_add_i32 m0, s45, 0x1c000
	v_lshl_add_u64 v[0:1], s[12:13], 0, v[140:141]
	global_load_lds_dwordx4 v[0:1], off
	v_lshl_add_u64 v[0:1], s[12:13], 0, v[144:145]
	s_add_i32 m0, s45, 0x1e000
	s_cmpk_lt_u32 s10, 0x100
	global_load_lds_dwordx4 v[0:1], off
	s_waitcnt vmcnt(8)
	s_barrier
	v_lshrrev_b32_e32 v1, 1, v8
	v_and_b32_e32 v1, 24, v1
	v_and_b32_e32 v0, 15, v8
	v_lshlrev_b32_e32 v2, 1, v1
	v_lshl_or_b32 v164, s1, 6, v0
	v_lshl_or_b32 v0, v0, 6, v2
	v_lshlrev_b32_e32 v2, 2, v8
	v_and_b32_e32 v2, 32, v2
	v_bitop3_b32 v3, v0, s11, v2 bitop3:0xde
	v_bitop3_b32 v165, v0, s15, v2 bitop3:0xde
	v_lshlrev_b32_e32 v0, 15, v9
	v_and_b32_e32 v0, 0xffff0000, v0
	v_or_b32_e32 v166, s14, v1
	v_lshl_add_u32 v0, v10, 12, v0
	v_and_b32_e32 v1, 1, v9
	v_lshl_or_b32 v0, v1, 6, v0
	v_lshl_add_u32 v146, v11, 1, v0
	v_lshlrev_b32_e32 v0, 15, v12
	v_and_b32_e32 v0, 0xffff0000, v0
	s_waitcnt vmcnt(6)
	v_lshl_add_u32 v0, v13, 12, v0
	v_and_b32_e32 v1, 1, v12
	s_cselect_b64 s[10:11], -1, 0
	v_lshl_or_b32 v0, v1, 6, v0
	s_add_i32 s64, 0, 0x10000
	s_add_i32 s65, 0, 0x14000
	s_sext_i32_i8 s66, s0
	s_ashr_i32 s63, s3, 31
	v_mov_b32_e32 v147, v141
	v_lshl_add_u32 v148, v14, 1, v0
	v_mov_b32_e32 v149, v141
	v_mov_b64_e32 v[150:151], 0x400
	v_mov_b64_e32 v[152:153], 0x3ff
	v_add_u32_e32 v167, s64, v165
	v_add_u32_e32 v168, s65, v165
	v_add_u32_e32 v169, 0, v3
	s_mov_b64 s[12:13], 0x40000
	s_mov_b64 s[14:15], 0x48000
	s_mov_b64 s[16:17], 0x50000
	s_mov_b64 s[18:19], 0x58000
	s_barrier
	s_branch .LBB0_445

; #define PG8_STAGE(bufoff, gbase, voff) do { _Pragma("unroll") for (int _i = 0; _i < 2; ++_i) \
;         __builtin_amdgcn_global_load_lds((const unsigned*)((const char*)(gbase) + (voff)[_i]), (PG8_LAS unsigned*)(lds + (bufoff) + ldsw + _i * 8192), 16, 0, 0); } while (0)
; #define PG8_WAIT_V(n) asm volatile("s_waitcnt vmcnt(" #n ")" ::: "memory")
; #define PG8_BAR __builtin_amdgcn_s_barrier()
; template <class Epi, class Sched, bool ALIGN_EPI = false, bool SP2 = false>
; __device__ __forceinline__ void gemm_phase(PG8_LAS unsigned char* lds, const Gemm g, const Sched& S, const Epi& E, int tid_in) {
;     ...
;     const int wid = __builtin_amdgcn_readfirstlane(tid >> 6), lane = tid & 63, wr = wid >> 2, wc = wid & 3, fr = lane & 15, fq = lane >> 4;
;     const int K = g.K, nt = K / BK;
;     unsigned voffA[2], voffB[2];
; #pragma unroll
;     for (int i = 0; i < 2; ++i) { int R, C; stage_rc(tid * 16 + i * 8192, R, C); const int Rb = Epi::PERM ? ((R & ~31) + perm32(R & 31)) : R;
;         voffA[i] = (unsigned)(R * K + C) * 2u; voffB[i] = (unsigned)(Rb * K + C) * 2u; }
;     const size_t kstep = (size_t)(BK * 2);
;     const size_t hstep = (size_t)HALF * K * 2;
;     const size_t tstep = 2 * hstep;
;     const unsigned ldsw = (unsigned)wid * 1024u;
;     const int aoff = lds_byte(wr * 64 + fr, fq * 8), boff = lds_byte(wc * 32 + fr, fq * 8);
;     ...
;     if constexpr (SP2) {
;         PG8_STAGE(PG8_SB(0, 0), cB, voffB); PG8_STAGE(PG8_SB(0, 1), cB + hstep, voffB); PG8_STAGE(PG8_SA(0, 0), cA, voffA); PG8_STAGE(PG8_SA(0, 1), cA + hstep, voffA);
;         if (wr == 1) PG8_BAR;
;         PG8_WAIT_V(2); PG8_BAR;
;         PG8_STAGE(PG8_SB(1, 0), cB + kstep, voffB); PG8_STAGE(PG8_SA(1, 0), cA + kstep, voffA); PG8_STAGE(PG8_SB(1, 1), cB + hstep + kstep, voffB);
;         PG8_WAIT_V(6); PG8_BAR;
.LBB0_474:
	s_lshl_b32 s6, s6, 5
	s_and_b32 s12, s6, 0x60
	s_mov_b64 s[6:7], 0x80
	s_add_i32 m0, s31, 0x18000
	v_lshl_add_u64 v[6:7], v[6:7], 0, s[6:7]
	s_lshl_b32 s9, s1, 13
	s_lshl_b32 s13, s12, 7
	global_load_lds_dwordx4 v[6:7], off
	v_lshl_add_u64 v[4:5], v[4:5], 0, s[6:7]
	s_add_i32 m0, s31, 0x1a000
	s_add_i32 s49, s31, 0x8000
	s_add_i32 s50, s31, 0xa000
	global_load_lds_dwordx4 v[4:5], off
	v_lshl_add_u64 v[0:1], v[0:1], 0, s[6:7]
	s_mov_b32 m0, s49
	s_add_u32 s10, s38, 0x80080
	global_load_lds_dwordx4 v[0:1], off
	v_lshl_add_u64 v[0:1], v[2:3], 0, s[6:7]
	s_mov_b32 m0, s50
	s_addc_u32 s11, s39, 0
	global_load_lds_dwordx4 v[0:1], off
	s_add_i32 m0, s31, 0x1c000
	v_lshl_add_u64 v[0:1], s[10:11], 0, v[130:131]
	global_load_lds_dwordx4 v[0:1], off
	v_lshl_add_u64 v[0:1], s[10:11], 0, v[134:135]
	s_add_i32 m0, s31, 0x1e000
	s_cmpk_lt_u32 s8, 0x100
	global_load_lds_dwordx4 v[0:1], off
	s_waitcnt vmcnt(8)
	s_barrier
	v_lshrrev_b32_e32 v1, 1, v215
	v_and_b32_e32 v1, 24, v1
	v_and_b32_e32 v0, 15, v215
	v_lshlrev_b32_e32 v2, 1, v1
	v_lshl_or_b32 v150, s1, 6, v0
	v_lshl_or_b32 v0, v0, 6, v2
	v_lshlrev_b32_e32 v2, 2, v215
	v_and_b32_e32 v2, 32, v2
	v_bitop3_b32 v3, v0, s9, v2 bitop3:0xde
	v_bitop3_b32 v151, v0, s13, v2 bitop3:0xde
	v_lshlrev_b32_e32 v0, 15, v8
	v_and_b32_e32 v0, 0xffff0000, v0
	v_or_b32_e32 v152, s12, v1
	v_lshl_add_u32 v0, v9, 12, v0
	v_and_b32_e32 v1, 1, v8
	v_lshl_or_b32 v0, v1, 6, v0
	v_lshl_add_u32 v136, v10, 1, v0
	v_lshlrev_b32_e32 v0, 15, v11
	v_and_b32_e32 v0, 0xffff0000, v0
	s_waitcnt vmcnt(6)
	v_lshl_add_u32 v0, v12, 12, v0
	v_and_b32_e32 v1, 1, v11
	s_cselect_b64 s[8:9], -1, 0
	v_lshl_or_b32 v0, v1, 6, v0
	s_add_i32 s52, 0, 0x10000
	s_add_i32 s53, 0, 0x14000
	s_sext_i32_i8 s54, s0
	s_ashr_i32 s51, s3, 31
	v_mov_b32_e32 v137, v131
	v_lshl_add_u32 v138, v13, 1, v0
	v_mov_b32_e32 v139, v131
	v_mov_b64_e32 v[140:141], 0x200
	v_mov_b64_e32 v[142:143], 0x1ff
	v_add_u32_e32 v153, s52, v151
	v_add_u32_e32 v154, s53, v151
	v_add_u32_e32 v155, 0, v3
	s_mov_b64 s[10:11], 0x20000
	s_mov_b64 s[12:13], 0x24000
	s_mov_b64 s[14:15], 0x28000
	s_mov_b64 s[16:17], 0x2c000
	s_barrier
	s_branch .LBB0_477
